# weight-conversion loops: dropped the loop-top store-drain wait (the previous tile's stores overlap the next tile's loads; counted waits stay conservative)
# speedup vs baseline: 1.0051x; 1.0051x over previous
; DI float conv_src(const float* src, int ld, int kind, int k, int n) {
;     ...
;   if (kind == CV_FFN) {
;     int tile = n >> 7, j = n & 127;
;     int col = j < 64 ? tile * 64 + j : DFF + tile * 64 + (j - 64);
;     return src[(size_t)k * ld + col];
; DI void conv_job(const float* src, int ld, int K, int N, int kind, const float* gain, u16* dst, char* smem, int rank, int nwork) {
;     ...
;   for (int tile = rank; tile < tk_n * tn_n; tile += nwork) {
;     const int tk = tile % tk_n, tn = tile / tk_n;
;     const int k0 = tk * 128, n0 = tn * 64;
;     const int nn = tid & 63;
;     float cv[16];
; #pragma unroll
;     for (int i = 0; i < 16; ++i) cv[i] = conv_src(src, ld, kind, k0 + (tid >> 6) + 8 * i, n0 + nn);
;     if (gain) {
;       float gv[16];
; #pragma unroll
;       for (int i = 0; i < 16; ++i) gv[i] = gain[k0 + (tid >> 6) + 8 * i];
; #pragma unroll
;       for (int i = 0; i < 16; ++i) cv[i] *= gv[i];
;     }
.LBB0_464:
	s_ashr_i32 s22, s21, 31
	s_lshr_b32 s22, s22, 29
	s_add_i32 s22, s21, s22
	s_ashr_i32 s26, s22, 3
	s_lshl_b32 s23, s26, 10
	s_lshl_b32 s22, s26, 6
	s_sub_i32 s27, s1, s23
	v_add_u32_e32 v16, s27, v19
	s_and_b32 s27, s22, 64
	s_cmp_eq_u32 s27, 0
	s_cselect_b64 vcc, -1, 0
	s_lshl_b32 s26, s26, 5
	v_or_b32_e32 v0, s27, v18
	s_andn2_b32 s26, s26, 63
	v_or_b32_e32 v1, s26, v0
	s_addk_i32 s26, 0xac0
	v_add_u32_e32 v0, s26, v0
	v_cndmask_b32_e32 v0, v0, v1, vcc
	v_ashrrev_i32_e32 v1, 31, v0
	v_lshl_add_u64 v[24:25], v[0:1], 2, s[14:15]
	v_mad_i64_i32 v[0:1], s[26:27], v16, s28, v[24:25]
	global_load_dword v0, v[0:1], off nt
	v_add_u32_e32 v1, 8, v16
	v_mad_i64_i32 v[2:3], s[26:27], v1, s28, v[24:25]
	global_load_dword v1, v[2:3], off nt
	v_add_u32_e32 v2, 16, v16
	v_mad_i64_i32 v[2:3], s[26:27], v2, s28, v[24:25]
	global_load_dword v2, v[2:3], off nt
	v_add_u32_e32 v3, 24, v16
	v_mad_i64_i32 v[4:5], s[26:27], v3, s28, v[24:25]
	global_load_dword v3, v[4:5], off nt
	v_add_u32_e32 v4, 32, v16
	v_mad_i64_i32 v[4:5], s[26:27], v4, s28, v[24:25]
	global_load_dword v4, v[4:5], off nt
	v_add_u32_e32 v5, 40, v16
	v_mad_i64_i32 v[6:7], s[26:27], v5, s28, v[24:25]
	global_load_dword v5, v[6:7], off nt
	v_add_u32_e32 v6, 48, v16
	v_mad_i64_i32 v[6:7], s[26:27], v6, s28, v[24:25]
	global_load_dword v6, v[6:7], off nt
	v_add_u32_e32 v7, 56, v16
	v_mad_i64_i32 v[8:9], s[26:27], v7, s28, v[24:25]
	global_load_dword v7, v[8:9], off nt
	v_add_u32_e32 v8, 64, v16
	v_mad_i64_i32 v[8:9], s[26:27], v8, s28, v[24:25]
	global_load_dword v8, v[8:9], off nt
	v_add_u32_e32 v9, 0x48, v16
	v_mad_i64_i32 v[10:11], s[26:27], v9, s28, v[24:25]
	global_load_dword v9, v[10:11], off nt
	v_add_u32_e32 v10, 0x50, v16
	v_mad_i64_i32 v[10:11], s[26:27], v10, s28, v[24:25]
	global_load_dword v10, v[10:11], off nt
	v_add_u32_e32 v11, 0x58, v16
	v_mad_i64_i32 v[12:13], s[26:27], v11, s28, v[24:25]
	global_load_dword v11, v[12:13], off nt
	v_add_u32_e32 v12, 0x60, v16
	v_mad_i64_i32 v[12:13], s[26:27], v12, s28, v[24:25]
	global_load_dword v12, v[12:13], off nt
	v_add_u32_e32 v13, 0x68, v16
	v_mad_i64_i32 v[14:15], s[26:27], v13, s28, v[24:25]
	global_load_dword v13, v[14:15], off nt
	v_add_u32_e32 v14, 0x70, v16
	v_mad_i64_i32 v[14:15], s[26:27], v14, s28, v[24:25]
	global_load_dword v14, v[14:15], off nt
	v_add_u32_e32 v15, 0x78, v16
	v_mad_i64_i32 v[24:25], s[26:27], v15, s28, v[24:25]
	global_load_dword v15, v[24:25], off nt
	s_andn2_b64 vcc, exec, s[12:13]
	s_cbranch_vccnz .LBB0_463
	v_ashrrev_i32_e32 v17, 31, v16
	v_lshl_add_u64 v[16:17], v[16:17], 2, s[18:19]
	global_load_dword v24, v[16:17], off nt
	global_load_dword v25, v[16:17], off offset:32 nt
	global_load_dword v26, v[16:17], off offset:64 nt
	global_load_dword v27, v[16:17], off offset:96 nt
	global_load_dword v28, v[16:17], off offset:128 nt
	global_load_dword v29, v[16:17], off offset:160 nt
	global_load_dword v30, v[16:17], off offset:192 nt
	global_load_dword v31, v[16:17], off offset:224 nt
	global_load_dword v32, v[16:17], off offset:256 nt
	global_load_dword v33, v[16:17], off offset:288 nt
	global_load_dword v34, v[16:17], off offset:320 nt
	global_load_dword v35, v[16:17], off offset:352 nt
	global_load_dword v36, v[16:17], off offset:384 nt
	global_load_dword v37, v[16:17], off offset:416 nt
	global_load_dword v38, v[16:17], off offset:448 nt
	global_load_dword v39, v[16:17], off offset:480 nt
	s_waitcnt vmcnt(14)
	v_pk_mul_f32 v[0:1], v[0:1], v[24:25]
	s_waitcnt vmcnt(12)
	v_pk_mul_f32 v[2:3], v[2:3], v[26:27]
	s_waitcnt vmcnt(10)
	v_pk_mul_f32 v[4:5], v[4:5], v[28:29]
	s_waitcnt vmcnt(8)
	v_pk_mul_f32 v[6:7], v[6:7], v[30:31]
	s_waitcnt vmcnt(6)
	v_pk_mul_f32 v[8:9], v[8:9], v[32:33]
	s_waitcnt vmcnt(4)
	v_pk_mul_f32 v[10:11], v[10:11], v[34:35]
	s_waitcnt vmcnt(2)
	v_pk_mul_f32 v[12:13], v[12:13], v[36:37]
	s_waitcnt vmcnt(0)
	v_pk_mul_f32 v[14:15], v[14:15], v[38:39]
	s_branch .LBB0_463

; DI float conv_src(const float* src, int ld, int kind, int k, int n) {
;     ...
;   if (kind == CV_FFN) {
;     int tile = n >> 7, j = n & 127;
;     int col = j < 64 ? tile * 64 + j : DFF + tile * 64 + (j - 64);
;     return src[(size_t)k * ld + col];
; DI void conv_job(const float* src, int ld, int K, int N, int kind, const float* gain, u16* dst, char* smem, int rank, int nwork) {
;     ...
;   for (int tile = rank; tile < tk_n * tn_n; tile += nwork) {
;     const int tk = tile % tk_n, tn = tile / tk_n;
;     const int k0 = tk * 128, n0 = tn * 64;
;     const int nn = tid & 63;
;     float cv[16];
; #pragma unroll
;     for (int i = 0; i < 16; ++i) cv[i] = conv_src(src, ld, kind, k0 + (tid >> 6) + 8 * i, n0 + nn);
;     if (gain) {
;       float gv[16];
; #pragma unroll
;       for (int i = 0; i < 16; ++i) gv[i] = gain[k0 + (tid >> 6) + 8 * i];
; #pragma unroll
;       for (int i = 0; i < 16; ++i) cv[i] *= gv[i];
;     }
.LBB0_472:
	s_ashr_i32 s20, s19, 31
	s_lshr_b32 s20, s20, 29
	s_add_i32 s20, s19, s20
	s_ashr_i32 s22, s20, 3
	s_lshl_b32 s21, s22, 10
	s_lshl_b32 s20, s22, 6
	s_sub_i32 s23, s1, s21
	v_add_u32_e32 v16, s23, v19
	s_and_b32 s23, s20, 64
	s_cmp_eq_u32 s23, 0
	s_cselect_b64 vcc, -1, 0
	s_lshl_b32 s22, s22, 5
	v_or_b32_e32 v0, s23, v18
	s_andn2_b32 s22, s22, 63
	v_or_b32_e32 v1, s22, v0
	s_addk_i32 s22, 0xac0
	v_add_u32_e32 v0, s22, v0
	v_cndmask_b32_e32 v0, v0, v1, vcc
	v_ashrrev_i32_e32 v1, 31, v0
	v_lshl_add_u64 v[24:25], v[0:1], 2, s[6:7]
	v_mad_i64_i32 v[0:1], s[22:23], v16, s28, v[24:25]
	global_load_dword v0, v[0:1], off nt
	v_add_u32_e32 v1, 8, v16
	v_mad_i64_i32 v[2:3], s[22:23], v1, s28, v[24:25]
	global_load_dword v1, v[2:3], off nt
	v_add_u32_e32 v2, 16, v16
	v_mad_i64_i32 v[2:3], s[22:23], v2, s28, v[24:25]
	global_load_dword v2, v[2:3], off nt
	v_add_u32_e32 v3, 24, v16
	v_mad_i64_i32 v[4:5], s[22:23], v3, s28, v[24:25]
	global_load_dword v3, v[4:5], off nt
	v_add_u32_e32 v4, 32, v16
	v_mad_i64_i32 v[4:5], s[22:23], v4, s28, v[24:25]
	global_load_dword v4, v[4:5], off nt
	v_add_u32_e32 v5, 40, v16
	v_mad_i64_i32 v[6:7], s[22:23], v5, s28, v[24:25]
	global_load_dword v5, v[6:7], off nt
	v_add_u32_e32 v6, 48, v16
	v_mad_i64_i32 v[6:7], s[22:23], v6, s28, v[24:25]
	global_load_dword v6, v[6:7], off nt
	v_add_u32_e32 v7, 56, v16
	v_mad_i64_i32 v[8:9], s[22:23], v7, s28, v[24:25]
	global_load_dword v7, v[8:9], off nt
	v_add_u32_e32 v8, 64, v16
	v_mad_i64_i32 v[8:9], s[22:23], v8, s28, v[24:25]
	global_load_dword v8, v[8:9], off nt
	v_add_u32_e32 v9, 0x48, v16
	v_mad_i64_i32 v[10:11], s[22:23], v9, s28, v[24:25]
	global_load_dword v9, v[10:11], off nt
	v_add_u32_e32 v10, 0x50, v16
	v_mad_i64_i32 v[10:11], s[22:23], v10, s28, v[24:25]
	global_load_dword v10, v[10:11], off nt
	v_add_u32_e32 v11, 0x58, v16
	v_mad_i64_i32 v[12:13], s[22:23], v11, s28, v[24:25]
	global_load_dword v11, v[12:13], off nt
	v_add_u32_e32 v12, 0x60, v16
	v_mad_i64_i32 v[12:13], s[22:23], v12, s28, v[24:25]
	global_load_dword v12, v[12:13], off nt
	v_add_u32_e32 v13, 0x68, v16
	v_mad_i64_i32 v[14:15], s[22:23], v13, s28, v[24:25]
	global_load_dword v13, v[14:15], off nt
	v_add_u32_e32 v14, 0x70, v16
	v_mad_i64_i32 v[14:15], s[22:23], v14, s28, v[24:25]
	global_load_dword v14, v[14:15], off nt
	v_add_u32_e32 v15, 0x78, v16
	v_mad_i64_i32 v[24:25], s[22:23], v15, s28, v[24:25]
	global_load_dword v15, v[24:25], off nt
	s_andn2_b64 vcc, exec, s[16:17]
	s_cbranch_vccnz .LBB0_471
	v_ashrrev_i32_e32 v17, 31, v16
	v_lshl_add_u64 v[16:17], v[16:17], 2, s[8:9]
	global_load_dword v24, v[16:17], off nt
	global_load_dword v25, v[16:17], off offset:32 nt
	global_load_dword v26, v[16:17], off offset:64 nt
	global_load_dword v27, v[16:17], off offset:96 nt
	global_load_dword v28, v[16:17], off offset:128 nt
	global_load_dword v29, v[16:17], off offset:160 nt
	global_load_dword v30, v[16:17], off offset:192 nt
	global_load_dword v31, v[16:17], off offset:224 nt
	global_load_dword v32, v[16:17], off offset:256 nt
	global_load_dword v33, v[16:17], off offset:288 nt
	global_load_dword v34, v[16:17], off offset:320 nt
	global_load_dword v35, v[16:17], off offset:352 nt
	global_load_dword v36, v[16:17], off offset:384 nt
	global_load_dword v37, v[16:17], off offset:416 nt
	global_load_dword v38, v[16:17], off offset:448 nt
	global_load_dword v39, v[16:17], off offset:480 nt
	s_waitcnt vmcnt(14)
	v_pk_mul_f32 v[0:1], v[0:1], v[24:25]
	s_waitcnt vmcnt(12)
	v_pk_mul_f32 v[2:3], v[2:3], v[26:27]
	s_waitcnt vmcnt(10)
	v_pk_mul_f32 v[4:5], v[4:5], v[28:29]
	s_waitcnt vmcnt(8)
	v_pk_mul_f32 v[6:7], v[6:7], v[30:31]
	s_waitcnt vmcnt(6)
	v_pk_mul_f32 v[8:9], v[8:9], v[32:33]
	s_waitcnt vmcnt(4)
	v_pk_mul_f32 v[10:11], v[10:11], v[34:35]
	s_waitcnt vmcnt(2)
	v_pk_mul_f32 v[12:13], v[12:13], v[36:37]
	s_waitcnt vmcnt(0)
	v_pk_mul_f32 v[14:15], v[14:15], v[38:39]
	s_branch .LBB0_471

; DI float conv_src(const float* src, int ld, int kind, int k, int n) {
;   if (kind == CV_ID) return src[(size_t)k * ld + n];
; DI void conv_job(const float* src, int ld, int K, int N, int kind, const float* gain, u16* dst, char* smem, int rank, int nwork) {
;     ...
;   for (int tile = rank; tile < tk_n * tn_n; tile += nwork) {
;     const int tk = tile % tk_n, tn = tile / tk_n;
;     const int k0 = tk * 128, n0 = tn * 64;
;     const int nn = tid & 63;
;     float cv[16];
; #pragma unroll
;     for (int i = 0; i < 16; ++i) cv[i] = conv_src(src, ld, kind, k0 + (tid >> 6) + 8 * i, n0 + nn);
;     if (gain) {
;       float gv[16];
; #pragma unroll
;       for (int i = 0; i < 16; ++i) gv[i] = gain[k0 + (tid >> 6) + 8 * i];
; #pragma unroll
;       for (int i = 0; i < 16; ++i) cv[i] *= gv[i];
;     }
.LBB0_522:
	s_lshr_b32 s19, s18, 31
	s_add_i32 s19, s18, s19
	s_ashr_i32 s19, s19, 1
	s_lshl_b32 s20, s19, 8
	s_lshl_b32 s19, s19, 6
	v_or_b32_e32 v0, s19, v18
	v_readlane_b32 s40, v252, 47
	s_sub_i32 s21, s14, s20
	v_ashrrev_i32_e32 v1, 31, v0
	v_readlane_b32 s42, v252, 49
	v_readlane_b32 s43, v252, 50
	v_add_u32_e32 v16, s21, v19
	s_movk_i32 s16, 0x4800
	v_lshl_add_u64 v[24:25], v[0:1], 2, s[42:43]
	v_mad_i64_i32 v[0:1], s[22:23], v16, s16, v[24:25]
	global_load_dword v0, v[0:1], off nt
	v_add_u32_e32 v1, 8, v16
	v_mad_i64_i32 v[2:3], s[22:23], v1, s16, v[24:25]
	global_load_dword v1, v[2:3], off nt
	v_add_u32_e32 v2, 16, v16
	v_mad_i64_i32 v[2:3], s[22:23], v2, s16, v[24:25]
	global_load_dword v2, v[2:3], off nt
	v_add_u32_e32 v3, 24, v16
	v_mad_i64_i32 v[4:5], s[22:23], v3, s16, v[24:25]
	global_load_dword v3, v[4:5], off nt
	v_add_u32_e32 v4, 32, v16
	v_mad_i64_i32 v[4:5], s[22:23], v4, s16, v[24:25]
	global_load_dword v4, v[4:5], off nt
	v_add_u32_e32 v5, 40, v16
	v_mad_i64_i32 v[6:7], s[22:23], v5, s16, v[24:25]
	global_load_dword v5, v[6:7], off nt
	v_add_u32_e32 v6, 48, v16
	v_mad_i64_i32 v[6:7], s[22:23], v6, s16, v[24:25]
	global_load_dword v6, v[6:7], off nt
	v_add_u32_e32 v7, 56, v16
	v_mad_i64_i32 v[8:9], s[22:23], v7, s16, v[24:25]
	global_load_dword v7, v[8:9], off nt
	v_add_u32_e32 v8, 64, v16
	v_mad_i64_i32 v[8:9], s[22:23], v8, s16, v[24:25]
	global_load_dword v8, v[8:9], off nt
	v_add_u32_e32 v9, 0x48, v16
	v_mad_i64_i32 v[10:11], s[22:23], v9, s16, v[24:25]
	global_load_dword v9, v[10:11], off nt
	v_add_u32_e32 v10, 0x50, v16
	v_mad_i64_i32 v[10:11], s[22:23], v10, s16, v[24:25]
	global_load_dword v10, v[10:11], off nt
	v_add_u32_e32 v11, 0x58, v16
	v_mad_i64_i32 v[12:13], s[22:23], v11, s16, v[24:25]
	global_load_dword v11, v[12:13], off nt
	v_add_u32_e32 v12, 0x60, v16
	v_mad_i64_i32 v[12:13], s[22:23], v12, s16, v[24:25]
	global_load_dword v12, v[12:13], off nt
	v_add_u32_e32 v13, 0x68, v16
	v_mad_i64_i32 v[14:15], s[22:23], v13, s16, v[24:25]
	global_load_dword v13, v[14:15], off nt
	v_add_u32_e32 v14, 0x70, v16
	v_mad_i64_i32 v[14:15], s[22:23], v14, s16, v[24:25]
	global_load_dword v14, v[14:15], off nt
	v_add_u32_e32 v15, 0x78, v16
	v_mad_i64_i32 v[24:25], s[22:23], v15, s16, v[24:25]
	global_load_dword v15, v[24:25], off nt
	v_readlane_b32 s16, v252, 63
	v_readlane_b32 s17, v253, 0
	v_readlane_b32 s41, v252, 48
	s_andn2_b64 vcc, exec, s[16:17]
	v_readlane_b32 s44, v252, 51
	v_readlane_b32 s45, v252, 52
	v_readlane_b32 s46, v252, 53
	v_readlane_b32 s47, v252, 54
	v_readlane_b32 s48, v252, 55
	v_readlane_b32 s49, v252, 56
	v_readlane_b32 s50, v252, 57
	v_readlane_b32 s51, v252, 58
	v_readlane_b32 s52, v252, 59
	v_readlane_b32 s53, v252, 60
	v_readlane_b32 s54, v252, 61
	v_readlane_b32 s55, v252, 62
	s_cbranch_vccnz .LBB0_521
	v_ashrrev_i32_e32 v17, 31, v16
	v_lshl_add_u64 v[16:17], v[16:17], 2, s[40:41]
	global_load_dword v24, v[16:17], off nt
	global_load_dword v25, v[16:17], off offset:32 nt
	global_load_dword v26, v[16:17], off offset:64 nt
	global_load_dword v27, v[16:17], off offset:96 nt
	global_load_dword v28, v[16:17], off offset:128 nt
	global_load_dword v29, v[16:17], off offset:160 nt
	global_load_dword v30, v[16:17], off offset:192 nt
	global_load_dword v31, v[16:17], off offset:224 nt
	global_load_dword v32, v[16:17], off offset:256 nt
	global_load_dword v33, v[16:17], off offset:288 nt
	global_load_dword v34, v[16:17], off offset:320 nt
	global_load_dword v35, v[16:17], off offset:352 nt
	global_load_dword v36, v[16:17], off offset:384 nt
	global_load_dword v37, v[16:17], off offset:416 nt
	global_load_dword v38, v[16:17], off offset:448 nt
	global_load_dword v39, v[16:17], off offset:480 nt
	s_waitcnt vmcnt(14)
	v_pk_mul_f32 v[0:1], v[0:1], v[24:25]
	s_waitcnt vmcnt(12)
	v_pk_mul_f32 v[2:3], v[2:3], v[26:27]
	s_waitcnt vmcnt(10)
	v_pk_mul_f32 v[4:5], v[4:5], v[28:29]
	s_waitcnt vmcnt(8)
	v_pk_mul_f32 v[6:7], v[6:7], v[30:31]
	s_waitcnt vmcnt(6)
	v_pk_mul_f32 v[8:9], v[8:9], v[32:33]
	s_waitcnt vmcnt(4)
	v_pk_mul_f32 v[10:11], v[10:11], v[34:35]
	s_waitcnt vmcnt(2)
	v_pk_mul_f32 v[12:13], v[12:13], v[36:37]
	s_waitcnt vmcnt(0)
	v_pk_mul_f32 v[14:15], v[14:15], v[38:39]
	s_branch .LBB0_521

; DI float conv_src(const float* src, int ld, int kind, int k, int n) {
;   if (kind == CV_ID) return src[(size_t)k * ld + n];
; DI void conv_job(const float* src, int ld, int K, int N, int kind, const float* gain, u16* dst, char* smem, int rank, int nwork) {
;     ...
;   for (int tile = rank; tile < tk_n * tn_n; tile += nwork) {
;     const int tk = tile % tk_n, tn = tile / tk_n;
;     const int k0 = tk * 128, n0 = tn * 64;
;     const int nn = tid & 63;
;     float cv[16];
; #pragma unroll
;     for (int i = 0; i < 16; ++i) cv[i] = conv_src(src, ld, kind, k0 + (tid >> 6) + 8 * i, n0 + nn);
;     if (gain) {
;       float gv[16];
; #pragma unroll
;       for (int i = 0; i < 16; ++i) gv[i] = gain[k0 + (tid >> 6) + 8 * i];
; #pragma unroll
;       for (int i = 0; i < 16; ++i) cv[i] *= gv[i];
;     }
.LBB0_565:
	s_ashr_i32 s8, s7, 31
	s_lshr_b32 s8, s8, 29
	s_add_i32 s8, s7, s8
	s_ashr_i32 s8, s8, 3
	s_lshl_b32 s9, s8, 10
	s_lshl_b32 s8, s8, 6
	v_or_b32_e32 v0, s8, v18
	v_readlane_b32 s40, v252, 47
	s_sub_i32 s14, s2, s9
	v_ashrrev_i32_e32 v1, 31, v0
	v_readlane_b32 s48, v252, 55
	v_readlane_b32 s49, v252, 56
	v_add_u32_e32 v16, s14, v19
	s_movk_i32 s16, 0x1400
	v_lshl_add_u64 v[24:25], v[0:1], 2, s[48:49]
	v_mad_i64_i32 v[0:1], s[14:15], v16, s16, v[24:25]
	global_load_dword v0, v[0:1], off nt
	v_add_u32_e32 v1, 8, v16
	v_mad_i64_i32 v[2:3], s[14:15], v1, s16, v[24:25]
	global_load_dword v1, v[2:3], off nt
	v_add_u32_e32 v2, 16, v16
	v_mad_i64_i32 v[2:3], s[14:15], v2, s16, v[24:25]
	global_load_dword v2, v[2:3], off nt
	v_add_u32_e32 v3, 24, v16
	v_mad_i64_i32 v[4:5], s[14:15], v3, s16, v[24:25]
	global_load_dword v3, v[4:5], off nt
	v_add_u32_e32 v4, 32, v16
	v_mad_i64_i32 v[4:5], s[14:15], v4, s16, v[24:25]
	global_load_dword v4, v[4:5], off nt
	v_add_u32_e32 v5, 40, v16
	v_mad_i64_i32 v[6:7], s[14:15], v5, s16, v[24:25]
	global_load_dword v5, v[6:7], off nt
	v_add_u32_e32 v6, 48, v16
	v_mad_i64_i32 v[6:7], s[14:15], v6, s16, v[24:25]
	global_load_dword v6, v[6:7], off nt
	v_add_u32_e32 v7, 56, v16
	v_mad_i64_i32 v[8:9], s[14:15], v7, s16, v[24:25]
	global_load_dword v7, v[8:9], off nt
	v_add_u32_e32 v8, 64, v16
	v_mad_i64_i32 v[8:9], s[14:15], v8, s16, v[24:25]
	global_load_dword v8, v[8:9], off nt
	v_add_u32_e32 v9, 0x48, v16
	v_mad_i64_i32 v[10:11], s[14:15], v9, s16, v[24:25]
	global_load_dword v9, v[10:11], off nt
	v_add_u32_e32 v10, 0x50, v16
	v_mad_i64_i32 v[10:11], s[14:15], v10, s16, v[24:25]
	global_load_dword v10, v[10:11], off nt
	v_add_u32_e32 v11, 0x58, v16
	v_mad_i64_i32 v[12:13], s[14:15], v11, s16, v[24:25]
	global_load_dword v11, v[12:13], off nt
	v_add_u32_e32 v12, 0x60, v16
	v_mad_i64_i32 v[12:13], s[14:15], v12, s16, v[24:25]
	global_load_dword v12, v[12:13], off nt
	v_add_u32_e32 v13, 0x68, v16
	v_mad_i64_i32 v[14:15], s[14:15], v13, s16, v[24:25]
	global_load_dword v13, v[14:15], off nt
	v_add_u32_e32 v14, 0x70, v16
	v_mad_i64_i32 v[14:15], s[14:15], v14, s16, v[24:25]
	global_load_dword v14, v[14:15], off nt
	v_add_u32_e32 v15, 0x78, v16
	v_mad_i64_i32 v[24:25], s[14:15], v15, s16, v[24:25]
	global_load_dword v15, v[24:25], off nt
	v_readlane_b32 s14, v252, 45
	v_readlane_b32 s15, v252, 46
	s_andn2_b64 vcc, exec, s[14:15]
	v_readlane_b32 s41, v252, 48
	v_readlane_b32 s42, v252, 49
	v_readlane_b32 s43, v252, 50
	v_readlane_b32 s44, v252, 51
	v_readlane_b32 s45, v252, 52
	v_readlane_b32 s46, v252, 53
	v_readlane_b32 s47, v252, 54
	v_readlane_b32 s50, v252, 57
	v_readlane_b32 s51, v252, 58
	v_readlane_b32 s52, v252, 59
	v_readlane_b32 s53, v252, 60
	v_readlane_b32 s54, v252, 61
	v_readlane_b32 s55, v252, 62
	s_cbranch_vccnz .LBB0_564
	v_ashrrev_i32_e32 v17, 31, v16
	v_lshl_add_u64 v[16:17], v[16:17], 2, s[4:5]
	global_load_dword v24, v[16:17], off nt
	global_load_dword v25, v[16:17], off offset:32 nt
	global_load_dword v26, v[16:17], off offset:64 nt
	global_load_dword v27, v[16:17], off offset:96 nt
	global_load_dword v28, v[16:17], off offset:128 nt
	global_load_dword v29, v[16:17], off offset:160 nt
	global_load_dword v30, v[16:17], off offset:192 nt
	global_load_dword v31, v[16:17], off offset:224 nt
	global_load_dword v32, v[16:17], off offset:256 nt
	global_load_dword v33, v[16:17], off offset:288 nt
	global_load_dword v34, v[16:17], off offset:320 nt
	global_load_dword v35, v[16:17], off offset:352 nt
	global_load_dword v36, v[16:17], off offset:384 nt
	global_load_dword v37, v[16:17], off offset:416 nt
	global_load_dword v38, v[16:17], off offset:448 nt
	global_load_dword v39, v[16:17], off offset:480 nt
	s_waitcnt vmcnt(14)
	v_pk_mul_f32 v[0:1], v[0:1], v[24:25]
	s_waitcnt vmcnt(12)
	v_pk_mul_f32 v[2:3], v[2:3], v[26:27]
	s_waitcnt vmcnt(10)
	v_pk_mul_f32 v[4:5], v[4:5], v[28:29]
	s_waitcnt vmcnt(8)
	v_pk_mul_f32 v[6:7], v[6:7], v[30:31]
	s_waitcnt vmcnt(6)
	v_pk_mul_f32 v[8:9], v[8:9], v[32:33]
	s_waitcnt vmcnt(4)
	v_pk_mul_f32 v[10:11], v[10:11], v[34:35]
	s_waitcnt vmcnt(2)
	v_pk_mul_f32 v[12:13], v[12:13], v[36:37]
	s_waitcnt vmcnt(0)
	v_pk_mul_f32 v[14:15], v[14:15], v[38:39]
	s_branch .LBB0_564

; DI float conv_src(const float* src, int ld, int kind, int k, int n) {
;   if (kind == CV_ID) return src[(size_t)k * ld + n];
; DI void conv_job(const float* src, int ld, int K, int N, int kind, const float* gain, u16* dst, char* smem, int rank, int nwork) {
;     ...
;   for (int tile = rank; tile < tk_n * tn_n; tile += nwork) {
;     const int tk = tile % tk_n, tn = tile / tk_n;
;     const int k0 = tk * 128, n0 = tn * 64;
;     const int nn = tid & 63;
;     float cv[16];
; #pragma unroll
;     for (int i = 0; i < 16; ++i) cv[i] = conv_src(src, ld, kind, k0 + (tid >> 6) + 8 * i, n0 + nn);
;     if (gain) {
;       float gv[16];
; #pragma unroll
;       for (int i = 0; i < 16; ++i) gv[i] = gain[k0 + (tid >> 6) + 8 * i];
; #pragma unroll
;       for (int i = 0; i < 16; ++i) cv[i] *= gv[i];
;     }
.LBB0_571:
	s_ashr_i32 s8, s0, 31
	s_lshr_b32 s8, s8, 29
	s_add_i32 s8, s0, s8
	s_ashr_i32 s8, s8, 3
	s_lshl_b32 s9, s8, 10
	s_lshl_b32 s8, s8, 6
	v_or_b32_e32 v0, s8, v18
	s_sub_i32 s14, s1, s9
	v_ashrrev_i32_e32 v1, 31, v0
	v_add_u32_e32 v16, s14, v19
	v_lshl_add_u64 v[24:25], v[0:1], 2, s[6:7]
	s_movk_i32 s16, 0x3000
	v_mad_i64_i32 v[0:1], s[14:15], v16, s16, v[24:25]
	global_load_dword v0, v[0:1], off nt
	v_add_u32_e32 v1, 8, v16
	v_mad_i64_i32 v[2:3], s[14:15], v1, s16, v[24:25]
	global_load_dword v1, v[2:3], off nt
	v_add_u32_e32 v2, 16, v16
	v_mad_i64_i32 v[2:3], s[14:15], v2, s16, v[24:25]
	global_load_dword v2, v[2:3], off nt
	v_add_u32_e32 v3, 24, v16
	v_mad_i64_i32 v[4:5], s[14:15], v3, s16, v[24:25]
	global_load_dword v3, v[4:5], off nt
	v_add_u32_e32 v4, 32, v16
	v_mad_i64_i32 v[4:5], s[14:15], v4, s16, v[24:25]
	global_load_dword v4, v[4:5], off nt
	v_add_u32_e32 v5, 40, v16
	v_mad_i64_i32 v[6:7], s[14:15], v5, s16, v[24:25]
	global_load_dword v5, v[6:7], off nt
	v_add_u32_e32 v6, 48, v16
	v_mad_i64_i32 v[6:7], s[14:15], v6, s16, v[24:25]
	global_load_dword v6, v[6:7], off nt
	v_add_u32_e32 v7, 56, v16
	v_mad_i64_i32 v[8:9], s[14:15], v7, s16, v[24:25]
	global_load_dword v7, v[8:9], off nt
	v_add_u32_e32 v8, 64, v16
	v_mad_i64_i32 v[8:9], s[14:15], v8, s16, v[24:25]
	global_load_dword v8, v[8:9], off nt
	v_add_u32_e32 v9, 0x48, v16
	v_mad_i64_i32 v[10:11], s[14:15], v9, s16, v[24:25]
	global_load_dword v9, v[10:11], off nt
	v_add_u32_e32 v10, 0x50, v16
	v_mad_i64_i32 v[10:11], s[14:15], v10, s16, v[24:25]
	global_load_dword v10, v[10:11], off nt
	v_add_u32_e32 v11, 0x58, v16
	v_mad_i64_i32 v[12:13], s[14:15], v11, s16, v[24:25]
	global_load_dword v11, v[12:13], off nt
	v_add_u32_e32 v12, 0x60, v16
	v_mad_i64_i32 v[12:13], s[14:15], v12, s16, v[24:25]
	global_load_dword v12, v[12:13], off nt
	v_add_u32_e32 v13, 0x68, v16
	v_mad_i64_i32 v[14:15], s[14:15], v13, s16, v[24:25]
	global_load_dword v13, v[14:15], off nt
	v_add_u32_e32 v14, 0x70, v16
	v_mad_i64_i32 v[14:15], s[14:15], v14, s16, v[24:25]
	global_load_dword v14, v[14:15], off nt
	v_add_u32_e32 v15, 0x78, v16
	v_mad_i64_i32 v[24:25], s[14:15], v15, s16, v[24:25]
	global_load_dword v15, v[24:25], off nt
	v_readlane_b32 s14, v252, 45
	v_readlane_b32 s15, v252, 46
	s_andn2_b64 vcc, exec, s[14:15]
	s_cbranch_vccnz .LBB0_570
	v_ashrrev_i32_e32 v17, 31, v16
	v_lshl_add_u64 v[16:17], v[16:17], 2, s[4:5]
	global_load_dword v24, v[16:17], off nt
	global_load_dword v25, v[16:17], off offset:32 nt
	global_load_dword v26, v[16:17], off offset:64 nt
	global_load_dword v27, v[16:17], off offset:96 nt
	global_load_dword v28, v[16:17], off offset:128 nt
	global_load_dword v29, v[16:17], off offset:160 nt
	global_load_dword v30, v[16:17], off offset:192 nt
	global_load_dword v31, v[16:17], off offset:224 nt
	global_load_dword v32, v[16:17], off offset:256 nt
	global_load_dword v33, v[16:17], off offset:288 nt
	global_load_dword v34, v[16:17], off offset:320 nt
	global_load_dword v35, v[16:17], off offset:352 nt
	global_load_dword v36, v[16:17], off offset:384 nt
	global_load_dword v37, v[16:17], off offset:416 nt
	global_load_dword v38, v[16:17], off offset:448 nt
	global_load_dword v39, v[16:17], off offset:480 nt
	s_waitcnt vmcnt(14)
	v_pk_mul_f32 v[0:1], v[0:1], v[24:25]
	s_waitcnt vmcnt(12)
	v_pk_mul_f32 v[2:3], v[2:3], v[26:27]
	s_waitcnt vmcnt(10)
	v_pk_mul_f32 v[4:5], v[4:5], v[28:29]
	s_waitcnt vmcnt(8)
	v_pk_mul_f32 v[6:7], v[6:7], v[30:31]
	s_waitcnt vmcnt(6)
	v_pk_mul_f32 v[8:9], v[8:9], v[32:33]
	s_waitcnt vmcnt(4)
	v_pk_mul_f32 v[10:11], v[10:11], v[34:35]
	s_waitcnt vmcnt(2)
	v_pk_mul_f32 v[12:13], v[12:13], v[36:37]
	s_waitcnt vmcnt(0)
	v_pk_mul_f32 v[14:15], v[14:15], v[38:39]
	s_branch .LBB0_570
